# tconv tile order: 4 tiles along n then all of k (dst rows written contiguously by neighbouring workgroups), on top of lru_carry + tconv pair prefetch
# baseline (speedup 1.0000x reference)
; #define PG8_LAS __attribute__((address_space(3)))
; __device__ void tconv(unsigned char* smem, const float* src, int ldsrc, int col0, int N, int K, u16* dst, int ldd) {
;     float* T = (float*)smem;
;     const int tid = threadIdx.x, tilesN = N >> 6, ntile = tilesN * (K >> 6);
;     const int lr = tid >> 4, lc = (tid & 15) * 4;
;     const int sn = tid >> 3, sk = (tid & 7) * 8;
;     int tile = blockIdx.x;
;     f32x4 v0 = {0.f, 0.f, 0.f, 0.f}, v1 = {0.f, 0.f, 0.f, 0.f};
;     if (tile < ntile) { const int tn = tile % tilesN, tk = tile / tilesN; const float* s = src + (size_t)(tk * 64 + lr) * ldsrc + col0 + tn * 64 + lc;
;         v0 = __builtin_nontemporal_load((const f32x4*)s); v1 = __builtin_nontemporal_load((const f32x4*)(s + (size_t)32 * ldsrc)); }
;     for (; tile < ntile; tile += gridDim.x) {
;         const int tn = tile % tilesN, tk = tile / tilesN;
; #pragma unroll
;         for (int j = 0; j < 4; ++j) { T[lr * 65 + lc + j] = v0[j]; T[(lr + 32) * 65 + lc + j] = v1[j]; }
;         asm volatile("s_waitcnt lgkmcnt(0)" ::: "memory"); __builtin_amdgcn_s_barrier(); asm volatile("" ::: "memory");
;         const int nx = tile + gridDim.x;
;         if (nx < ntile) { const int tn2 = nx % tilesN, tk2 = nx / tilesN; const float* s = src + (size_t)(tk2 * 64 + lr) * ldsrc + col0 + tn2 * 64 + lc;
;             v0 = __builtin_nontemporal_load((const f32x4*)s); v1 = __builtin_nontemporal_load((const f32x4*)(s + (size_t)32 * ldsrc)); }
;         float f[8];
; #pragma unroll
;         for (int j = 0; j < 8; ++j) f[j] = T[(sk + j) * 65 + sn];
;         *(u32x4*)(dst + (size_t)(tn * 64 + sn) * ldd + tk * 64 + sk) = pack8(f);
;         asm volatile("s_waitcnt lgkmcnt(0)" ::: "memory"); __builtin_amdgcn_s_barrier(); asm volatile("" ::: "memory");
;     }
;     __syncthreads();
; }
; __global__ void __launch_bounds__(512, 2) mega(Params p) {
;     extern __shared__ __attribute__((aligned(16))) unsigned char smem[];
;     cg::grid_group grid = cg::this_grid();
;     const int lo = p.ph_lo, hi = p.ph_hi;
;     ...
;     unsigned long long tp0 = (PROBE_PH >= 0) ? __builtin_amdgcn_s_memrealtime() : 0ull, tp1 = 0;
;     unsigned char* ws = p.ws;
;     PG8_LAS unsigned char* glds = (PG8_LAS unsigned char*)smem;
;     if (IN(0)) for (int rep_ = 0; rep_ < 1 + (REP_MASK & 1); ++rep_) {
;         tconv(smem, p.in[2], 8192, 0, 8192, 2048, (u16*)(ws + OFF_W0IN), 2048);
_Z4mega6Params:
	s_mov_b32 s100, 0
	s_mov_b32 s70, s2
	s_mov_b64 s[16:17], s[0:1]
	s_load_dwordx2 s[88:89], s[0:1], 0x0
	s_nop 0
	s_load_dwordx16 s[0:15], s[16:17], 0x10
	s_add_u32 s68, s16, 0x160
	s_addc_u32 s69, s17, 0
	s_waitcnt lgkmcnt(0)
	v_writelane_b32 v251, s0, 0
	s_nop 1
	v_writelane_b32 v251, s1, 1
	v_writelane_b32 v251, s2, 2
	v_writelane_b32 v251, s3, 3
	v_writelane_b32 v251, s4, 4
	v_writelane_b32 v251, s5, 5
	v_writelane_b32 v251, s6, 6
	v_writelane_b32 v251, s7, 7
	v_writelane_b32 v251, s8, 8
	v_writelane_b32 v251, s9, 9
	v_writelane_b32 v251, s10, 10
	v_writelane_b32 v251, s11, 11
	v_writelane_b32 v251, s12, 12
	v_writelane_b32 v251, s13, 13
	v_writelane_b32 v251, s14, 14
	v_writelane_b32 v251, s15, 15
	s_load_dwordx16 s[72:87], s[16:17], 0x50
	s_load_dwordx4 s[64:67], s[16:17], 0x150
	s_load_dwordx16 s[0:15], s[16:17], 0x90
	s_waitcnt lgkmcnt(0)
	s_cmp_lt_i32 s66, 1
	v_writelane_b32 v251, s0, 16
	s_nop 1
	v_writelane_b32 v251, s1, 17
	v_writelane_b32 v251, s2, 18
	v_writelane_b32 v251, s3, 19
	v_writelane_b32 v251, s4, 20
	v_writelane_b32 v251, s5, 21
	v_writelane_b32 v251, s6, 22
	v_writelane_b32 v251, s7, 23
	v_writelane_b32 v251, s8, 24
	v_writelane_b32 v251, s9, 25
	v_writelane_b32 v251, s10, 26
	v_writelane_b32 v251, s11, 27
	v_writelane_b32 v251, s12, 28
	v_writelane_b32 v251, s13, 29
	v_writelane_b32 v251, s14, 30
	v_writelane_b32 v251, s15, 31
	v_writelane_b32 v251, s16, 32
	s_load_dword s62, s[16:17], 0x160
	s_cselect_b64 s[0:1], -1, 0
	s_cmp_gt_i32 s67, 0
	s_cselect_b64 s[2:3], -1, 0
	s_and_b64 s[0:1], s[0:1], s[2:3]
	s_andn2_b64 vcc, exec, s[0:1]
	v_writelane_b32 v251, s17, 33
	s_cbranch_vccnz .LBB0_25
	v_and_b32_e32 v1, 0x3ff, v0
	v_lshlrev_b32_e32 v14, 2, v1
	v_bfe_u32 v16, v0, 4, 6
	v_and_b32_e32 v2, 60, v14
	v_lshlrev_b32_e32 v15, 3, v1
	v_lshlrev_b32_e32 v10, 2, v2
	v_mul_u32_u24_e32 v2, 0x41, v16
	v_bfe_u32 v17, v0, 3, 7
	v_and_b32_e32 v19, 56, v15
	v_lshlrev_b32_e32 v2, 2, v2
	s_cmpk_gt_i32 s70, 0xfff
	v_mov_b32_e32 v11, 0
	v_add3_u32 v18, 0, v10, v2
	v_add3_u32 v20, 0, v2, v10
	v_lshl_add_u32 v21, v17, 2, 0
	v_mul_u32_u24_e32 v22, 0x104, v19
	s_cbranch_scc1 .LBB0_8
	s_waitcnt vmcnt(0) lgkmcnt(0)
	s_barrier
	v_readlane_b32 s56, v251, 32
	v_readlane_b32 s57, v251, 33
	v_and_b32_e32 v142, 0x3ff, v0
	v_lshrrev_b32_e32 v153, 4, v142
	v_and_b32_e32 v154, 15, v142
	v_lshlrev_b32_e32 v154, 4, v154
	v_lshlrev_b32_e32 v143, 15, v153
	s_load_dwordx2 s[40:41], s[56:57], 0x10
	v_add_u32_e32 v143, v143, v154
	v_mul_u32_u24_e32 v145, 0x104, v153
	v_add_u32_e32 v145, v145, v154
	v_add_u32_e32 v146, 0x2080, v145
	v_add_u32_e32 v147, 0x4100, v145
	v_add_u32_e32 v148, 0x6180, v145
	v_lshrrev_b32_e32 v153, 3, v142
	v_and_b32_e32 v154, 7, v142
	v_mul_u32_u24_e32 v149, 0x820, v154
	v_lshl_add_u32 v149, v153, 2, v149
	v_add_u32_e32 v150, 0x400, v149
	v_add_u32_e32 v151, 0x4100, v149
	v_add_u32_e32 v152, 0x4500, v149
	v_lshlrev_b32_e32 v144, 12, v153
	v_lshl_add_u32 v144, v154, 4, v144
	s_add_u32 s44, s64, 0x1c000000
	s_addc_u32 s45, s65, 0
	s_lshl_b32 s54, s62, 1
	s_mov_b32 s46, s70
	s_waitcnt lgkmcnt(0)
	s_add_u32 s42, s40, 0x100000
	s_addc_u32 s43, s41, 0
	s_add_i32 s47, s46, s62
	s_cmpk_lt_i32 s47, 0x1000
	s_cselect_b32 s47, s47, s46
	s_lshr_b32 s53, s46, 7
	s_and_b32 s52, s46, 3
	s_lshl_b32 s53, s53, 2
	s_or_b32 s52, s52, s53
	s_bfe_u32 s53, s46, 0x50002
	s_lshl_b32 s52, s52, 8
	s_lshl_b32 s53, s53, 21
	s_add_i32 s48, s52, s53
	s_lshr_b32 s53, s47, 7
	s_and_b32 s52, s47, 3
	s_lshl_b32 s53, s53, 2
	s_or_b32 s52, s52, s53
	s_bfe_u32 s53, s47, 0x50002
	s_lshl_b32 s52, s52, 8
	s_lshl_b32 s53, s53, 21
	s_add_i32 s49, s52, s53
	v_add_u32_e32 v153, s48, v143
	v_add_u32_e32 v172, s49, v143
	global_load_dwordx4 v[70:73], v153, s[40:41] nt
	global_load_dwordx4 v[74:77], v153, s[42:43] nt
	global_load_dwordx4 v[78:81], v172, s[40:41] nt
	global_load_dwordx4 v[82:85], v172, s[42:43] nt
	s_waitcnt vmcnt(0)
TCV1_body:
	ds_write2_b32 v145, v70, v71 offset1:1
	ds_write2_b32 v145, v72, v73 offset0:2 offset1:3
	ds_write2_b32 v146, v74, v75 offset1:1
	ds_write2_b32 v146, v76, v77 offset0:2 offset1:3
	ds_write2_b32 v147, v78, v79 offset1:1
	ds_write2_b32 v147, v80, v81 offset0:2 offset1:3
	ds_write2_b32 v148, v82, v83 offset1:1
	ds_write2_b32 v148, v84, v85 offset0:2 offset1:3
	s_lshr_b32 s53, s46, 7
	s_and_b32 s52, s46, 3
	s_lshl_b32 s53, s53, 2
	s_or_b32 s52, s52, s53
	s_bfe_u32 s53, s46, 0x50002
	s_lshl_b32 s52, s52, 18
	s_lshl_b32 s53, s53, 7
	s_add_i32 s50, s52, s53
	s_lshr_b32 s53, s47, 7
	s_and_b32 s52, s47, 3
	s_lshl_b32 s53, s53, 2
	s_or_b32 s52, s52, s53
	s_bfe_u32 s53, s47, 0x50002
	s_lshl_b32 s52, s52, 18
	s_lshl_b32 s53, s53, 7
	s_add_i32 s51, s52, s53
	s_waitcnt lgkmcnt(0)
	s_barrier
	s_add_i32 s46, s46, s54
	s_cmpk_lt_i32 s46, 0x1000
	s_cbranch_scc0 TCV1_noload
	s_add_i32 s47, s46, s62
	s_cmpk_lt_i32 s47, 0x1000
	s_cselect_b32 s47, s47, s46
	s_lshr_b32 s53, s46, 7
	s_and_b32 s52, s46, 3
	s_lshl_b32 s53, s53, 2
	s_or_b32 s52, s52, s53
	s_bfe_u32 s53, s46, 0x50002
	s_lshl_b32 s52, s52, 8
	s_lshl_b32 s53, s53, 21
	s_add_i32 s48, s52, s53
	s_lshr_b32 s53, s47, 7
	s_and_b32 s52, s47, 3
	s_lshl_b32 s53, s53, 2
	s_or_b32 s52, s52, s53
	s_bfe_u32 s53, s47, 0x50002
	s_lshl_b32 s52, s52, 8
	s_lshl_b32 s53, s53, 21
	s_add_i32 s49, s52, s53
	v_add_u32_e32 v153, s48, v143
	v_add_u32_e32 v172, s49, v143
	global_load_dwordx4 v[70:73], v153, s[40:41] nt
	global_load_dwordx4 v[74:77], v153, s[42:43] nt
	global_load_dwordx4 v[78:81], v172, s[40:41] nt
	global_load_dwordx4 v[82:85], v172, s[42:43] nt

; __device__ __forceinline__ u32x4 pack8(const float* f) { u32x4 w; w.x = pk2(f[0], f[1]); w.y = pk2(f[2], f[3]); w.z = pk2(f[4], f[5]); w.w = pk2(f[6], f[7]); return w; }
; __device__ void tconv(unsigned char* smem, const float* src, int ldsrc, int col0, int N, int K, u16* dst, int ldd) {
;     float* T = (float*)smem;
;     const int tid = threadIdx.x, tilesN = N >> 6, ntile = tilesN * (K >> 6);
;     const int lr = tid >> 4, lc = (tid & 15) * 4;
;     const int sn = tid >> 3, sk = (tid & 7) * 8;
;     int tile = blockIdx.x;
;     f32x4 v0 = {0.f, 0.f, 0.f, 0.f}, v1 = {0.f, 0.f, 0.f, 0.f};
;     if (tile < ntile) { const int tn = tile % tilesN, tk = tile / tilesN; const float* s = src + (size_t)(tk * 64 + lr) * ldsrc + col0 + tn * 64 + lc;
;         v0 = __builtin_nontemporal_load((const f32x4*)s); v1 = __builtin_nontemporal_load((const f32x4*)(s + (size_t)32 * ldsrc)); }
;     for (; tile < ntile; tile += gridDim.x) {
;         const int tn = tile % tilesN, tk = tile / tilesN;
; #pragma unroll
;         for (int j = 0; j < 4; ++j) { T[lr * 65 + lc + j] = v0[j]; T[(lr + 32) * 65 + lc + j] = v1[j]; }
;         asm volatile("s_waitcnt lgkmcnt(0)" ::: "memory"); __builtin_amdgcn_s_barrier(); asm volatile("" ::: "memory");
;         const int nx = tile + gridDim.x;
;         if (nx < ntile) { const int tn2 = nx % tilesN, tk2 = nx / tilesN; const float* s = src + (size_t)(tk2 * 64 + lr) * ldsrc + col0 + tn2 * 64 + lc;
;             v0 = __builtin_nontemporal_load((const f32x4*)s); v1 = __builtin_nontemporal_load((const f32x4*)(s + (size_t)32 * ldsrc)); }
;         float f[8];
; #pragma unroll
;         for (int j = 0; j < 8; ++j) f[j] = T[(sk + j) * 65 + sn];
;         *(u32x4*)(dst + (size_t)(tn * 64 + sn) * ldd + tk * 64 + sk) = pack8(f);
;         asm volatile("s_waitcnt lgkmcnt(0)" ::: "memory"); __builtin_amdgcn_s_barrier(); asm volatile("" ::: "memory");
;     }
;     __syncthreads();
; }
.LBB0_8:
	s_cmpk_gt_i32 s70, 0x7ff
	s_waitcnt lgkmcnt(0)
	s_barrier
	s_cbranch_scc1 .LBB0_15
	s_waitcnt vmcnt(0) lgkmcnt(0)
	s_barrier
	v_readlane_b32 s56, v251, 32
	v_readlane_b32 s57, v251, 33
	v_and_b32_e32 v142, 0x3ff, v0
	v_lshrrev_b32_e32 v153, 4, v142
	v_and_b32_e32 v154, 15, v142
	v_lshlrev_b32_e32 v154, 4, v154
	v_lshlrev_b32_e32 v143, 13, v153
	s_load_dwordx2 s[40:41], s[56:57], 0xa8
	v_add_u32_e32 v143, v143, v154
	v_mul_u32_u24_e32 v145, 0x104, v153
	v_add_u32_e32 v145, v145, v154
	v_add_u32_e32 v146, 0x2080, v145
	v_add_u32_e32 v147, 0x4100, v145
	v_add_u32_e32 v148, 0x6180, v145
	v_lshrrev_b32_e32 v153, 3, v142
	v_and_b32_e32 v154, 7, v142
	v_mul_u32_u24_e32 v149, 0x820, v154
	v_lshl_add_u32 v149, v153, 2, v149
	v_add_u32_e32 v150, 0x400, v149
	v_add_u32_e32 v151, 0x4100, v149
	v_add_u32_e32 v152, 0x4500, v149
	v_lshlrev_b32_e32 v144, 13, v153
	v_lshl_add_u32 v144, v154, 4, v144
	s_add_u32 s44, s64, 0x1e000000
	s_addc_u32 s45, s65, 0
	s_lshl_b32 s54, s62, 1
	s_mov_b32 s46, s70
	s_waitcnt lgkmcnt(0)
	s_add_u32 s42, s40, 0x40000
	s_addc_u32 s43, s41, 0
	s_add_i32 s47, s46, s62
	s_cmpk_lt_i32 s47, 0x800
	s_cselect_b32 s47, s47, s46
	s_lshr_b32 s53, s46, 8
	s_and_b32 s52, s46, 3
	s_lshl_b32 s53, s53, 2
	s_or_b32 s52, s52, s53
	s_bfe_u32 s53, s46, 0x60002
	s_lshl_b32 s52, s52, 8
	s_lshl_b32 s53, s53, 19
	s_add_i32 s48, s52, s53
	s_lshr_b32 s53, s47, 8
	s_and_b32 s52, s47, 3
	s_lshl_b32 s53, s53, 2
	s_or_b32 s52, s52, s53
	s_bfe_u32 s53, s47, 0x60002
	s_lshl_b32 s52, s52, 8
	s_lshl_b32 s53, s53, 19
	s_add_i32 s49, s52, s53
	v_add_u32_e32 v153, s48, v143
	v_add_u32_e32 v172, s49, v143
	global_load_dwordx4 v[70:73], v153, s[40:41] nt
	global_load_dwordx4 v[74:77], v153, s[42:43] nt
	global_load_dwordx4 v[78:81], v172, s[40:41] nt
	global_load_dwordx4 v[82:85], v172, s[42:43] nt
	s_waitcnt vmcnt(0)
TCV2_body:
	ds_write2_b32 v145, v70, v71 offset1:1
	ds_write2_b32 v145, v72, v73 offset0:2 offset1:3
	ds_write2_b32 v146, v74, v75 offset1:1
	ds_write2_b32 v146, v76, v77 offset0:2 offset1:3
	ds_write2_b32 v147, v78, v79 offset1:1
	ds_write2_b32 v147, v80, v81 offset0:2 offset1:3
	ds_write2_b32 v148, v82, v83 offset1:1
	ds_write2_b32 v148, v84, v85 offset0:2 offset1:3
	s_lshr_b32 s53, s46, 8
	s_and_b32 s52, s46, 3
	s_lshl_b32 s53, s53, 2
	s_or_b32 s52, s52, s53
	s_bfe_u32 s53, s46, 0x60002
	s_lshl_b32 s52, s52, 19
	s_lshl_b32 s53, s53, 7
	s_add_i32 s50, s52, s53
	s_lshr_b32 s53, s47, 8
	s_and_b32 s52, s47, 3
	s_lshl_b32 s53, s53, 2
	s_or_b32 s52, s52, s53
	s_bfe_u32 s53, s47, 0x60002
	s_lshl_b32 s52, s52, 19
	s_lshl_b32 s53, s53, 7
	s_add_i32 s51, s52, s53
	s_waitcnt lgkmcnt(0)
	s_barrier
	s_add_i32 s46, s46, s54
	s_cmpk_lt_i32 s46, 0x800
	s_cbranch_scc0 TCV2_noload
	s_add_i32 s47, s46, s62
	s_cmpk_lt_i32 s47, 0x800
	s_cselect_b32 s47, s47, s46
	s_lshr_b32 s53, s46, 8
	s_and_b32 s52, s46, 3
	s_lshl_b32 s53, s53, 2
	s_or_b32 s52, s52, s53
	s_bfe_u32 s53, s46, 0x60002
	s_lshl_b32 s52, s52, 8
	s_lshl_b32 s53, s53, 19
	s_add_i32 s48, s52, s53
	s_lshr_b32 s53, s47, 8
	s_and_b32 s52, s47, 3
	s_lshl_b32 s53, s53, 2
	s_or_b32 s52, s52, s53
	s_bfe_u32 s53, s47, 0x60002
	s_lshl_b32 s52, s52, 8
	s_lshl_b32 s53, s53, 19
	s_add_i32 s49, s52, s53
	v_add_u32_e32 v153, s48, v143
	v_add_u32_e32 v172, s49, v143
	global_load_dwordx4 v[70:73], v153, s[40:41] nt
	global_load_dwordx4 v[74:77], v153, s[42:43] nt
	global_load_dwordx4 v[78:81], v172, s[40:41] nt
	global_load_dwordx4 v[82:85], v172, s[42:43] nt

; __device__ __forceinline__ u32x4 pack8(const float* f) { u32x4 w; w.x = pk2(f[0], f[1]); w.y = pk2(f[2], f[3]); w.z = pk2(f[4], f[5]); w.w = pk2(f[6], f[7]); return w; }
; __device__ void tconv(unsigned char* smem, const float* src, int ldsrc, int col0, int N, int K, u16* dst, int ldd) {
;     float* T = (float*)smem;
;     const int tid = threadIdx.x, tilesN = N >> 6, ntile = tilesN * (K >> 6);
;     const int lr = tid >> 4, lc = (tid & 15) * 4;
;     const int sn = tid >> 3, sk = (tid & 7) * 8;
;     int tile = blockIdx.x;
;     f32x4 v0 = {0.f, 0.f, 0.f, 0.f}, v1 = {0.f, 0.f, 0.f, 0.f};
;     if (tile < ntile) { const int tn = tile % tilesN, tk = tile / tilesN; const float* s = src + (size_t)(tk * 64 + lr) * ldsrc + col0 + tn * 64 + lc;
;         v0 = __builtin_nontemporal_load((const f32x4*)s); v1 = __builtin_nontemporal_load((const f32x4*)(s + (size_t)32 * ldsrc)); }
;     for (; tile < ntile; tile += gridDim.x) {
;         const int tn = tile % tilesN, tk = tile / tilesN;
; #pragma unroll
;         for (int j = 0; j < 4; ++j) { T[lr * 65 + lc + j] = v0[j]; T[(lr + 32) * 65 + lc + j] = v1[j]; }
;         asm volatile("s_waitcnt lgkmcnt(0)" ::: "memory"); __builtin_amdgcn_s_barrier(); asm volatile("" ::: "memory");
;         const int nx = tile + gridDim.x;
;         if (nx < ntile) { const int tn2 = nx % tilesN, tk2 = nx / tilesN; const float* s = src + (size_t)(tk2 * 64 + lr) * ldsrc + col0 + tn2 * 64 + lc;
;             v0 = __builtin_nontemporal_load((const f32x4*)s); v1 = __builtin_nontemporal_load((const f32x4*)(s + (size_t)32 * ldsrc)); }
;         float f[8];
; #pragma unroll
;         for (int j = 0; j < 8; ++j) f[j] = T[(sk + j) * 65 + sn];
;         *(u32x4*)(dst + (size_t)(tn * 64 + sn) * ldd + tk * 64 + sk) = pack8(f);
;         asm volatile("s_waitcnt lgkmcnt(0)" ::: "memory"); __builtin_amdgcn_s_barrier(); asm volatile("" ::: "memory");
;     }
;     __syncthreads();
; }
.LBB0_617:
	s_cmpk_gt_i32 s70, 0xfff
	s_cbranch_scc1 .LBB0_624
	s_waitcnt vmcnt(0) lgkmcnt(0)
	s_barrier
	v_readlane_b32 s56, v251, 32
	v_readlane_b32 s57, v251, 33
	v_and_b32_e32 v142, 0x3ff, v0
	v_lshrrev_b32_e32 v153, 4, v142
	v_and_b32_e32 v154, 15, v142
	v_lshlrev_b32_e32 v154, 4, v154
	v_lshlrev_b32_e32 v143, 16, v153
	s_load_dwordx2 s[40:41], s[56:57], 0xc0
	v_add_u32_e32 v143, v143, v154
	v_mul_u32_u24_e32 v145, 0x104, v153
	v_add_u32_e32 v145, v145, v154
	v_add_u32_e32 v146, 0x2080, v145
	v_add_u32_e32 v147, 0x4100, v145
	v_add_u32_e32 v148, 0x6180, v145
	v_lshrrev_b32_e32 v153, 3, v142
	v_and_b32_e32 v154, 7, v142
	v_mul_u32_u24_e32 v149, 0x820, v154
	v_lshl_add_u32 v149, v153, 2, v149
	v_add_u32_e32 v150, 0x400, v149
	v_add_u32_e32 v151, 0x4100, v149
	v_add_u32_e32 v152, 0x4500, v149
	v_lshlrev_b32_e32 v144, 12, v153
	v_lshl_add_u32 v144, v154, 4, v144
	s_add_u32 s44, s64, 0x1c000000
	s_addc_u32 s45, s65, 0
	s_lshl_b32 s54, s62, 1
	s_mov_b32 s46, s70
	s_waitcnt lgkmcnt(0)
	s_add_u32 s42, s40, 0x200000
	s_addc_u32 s43, s41, 0
	s_add_i32 s47, s46, s62
	s_cmpk_lt_i32 s47, 0x1000
	s_cselect_b32 s47, s47, s46
	s_lshr_b32 s53, s46, 7
	s_and_b32 s52, s46, 3
	s_lshl_b32 s53, s53, 2
	s_or_b32 s52, s52, s53
	s_bfe_u32 s53, s46, 0x50002
	s_lshl_b32 s52, s52, 8
	s_lshl_b32 s53, s53, 22
	s_add_i32 s48, s52, s53
	s_lshr_b32 s53, s47, 7
	s_and_b32 s52, s47, 3
	s_lshl_b32 s53, s53, 2
	s_or_b32 s52, s52, s53
	s_bfe_u32 s53, s47, 0x50002
	s_lshl_b32 s52, s52, 8
	s_lshl_b32 s53, s53, 22
	s_add_i32 s49, s52, s53
	v_add_u32_e32 v153, s48, v143
	v_add_u32_e32 v172, s49, v143
	global_load_dwordx4 v[70:73], v153, s[40:41] nt
	global_load_dwordx4 v[74:77], v153, s[42:43] nt
	global_load_dwordx4 v[78:81], v172, s[40:41] nt
	global_load_dwordx4 v[82:85], v172, s[42:43] nt
	s_waitcnt vmcnt(0)
TCV3_body:
	ds_write2_b32 v145, v70, v71 offset1:1
	ds_write2_b32 v145, v72, v73 offset0:2 offset1:3
	ds_write2_b32 v146, v74, v75 offset1:1
	ds_write2_b32 v146, v76, v77 offset0:2 offset1:3
	ds_write2_b32 v147, v78, v79 offset1:1
	ds_write2_b32 v147, v80, v81 offset0:2 offset1:3
	ds_write2_b32 v148, v82, v83 offset1:1
	ds_write2_b32 v148, v84, v85 offset0:2 offset1:3
	s_lshr_b32 s53, s46, 7
	s_and_b32 s52, s46, 3
	s_lshl_b32 s53, s53, 2
	s_or_b32 s52, s52, s53
	s_bfe_u32 s53, s46, 0x50002
	s_lshl_b32 s52, s52, 18
	s_lshl_b32 s53, s53, 7
	s_add_i32 s50, s52, s53
	s_lshr_b32 s53, s47, 7
	s_and_b32 s52, s47, 3
	s_lshl_b32 s53, s53, 2
	s_or_b32 s52, s52, s53
	s_bfe_u32 s53, s47, 0x50002
	s_lshl_b32 s52, s52, 18
	s_lshl_b32 s53, s53, 7
	s_add_i32 s51, s52, s53
	s_waitcnt lgkmcnt(0)
	s_barrier
	s_add_i32 s46, s46, s54
	s_cmpk_lt_i32 s46, 0x1000
	s_cbranch_scc0 TCV3_noload
	s_add_i32 s47, s46, s62
	s_cmpk_lt_i32 s47, 0x1000
	s_cselect_b32 s47, s47, s46
	s_lshr_b32 s53, s46, 7
	s_and_b32 s52, s46, 3
	s_lshl_b32 s53, s53, 2
	s_or_b32 s52, s52, s53
	s_bfe_u32 s53, s46, 0x50002
	s_lshl_b32 s52, s52, 8
	s_lshl_b32 s53, s53, 22
	s_add_i32 s48, s52, s53
	s_lshr_b32 s53, s47, 7
	s_and_b32 s52, s47, 3
	s_lshl_b32 s53, s53, 2
	s_or_b32 s52, s52, s53
	s_bfe_u32 s53, s47, 0x50002
	s_lshl_b32 s52, s52, 8
	s_lshl_b32 s53, s53, 22
	s_add_i32 s49, s52, s53
	v_add_u32_e32 v153, s48, v143
	v_add_u32_e32 v172, s49, v143
	global_load_dwordx4 v[70:73], v153, s[40:41] nt
	global_load_dwordx4 v[74:77], v153, s[42:43] nt
	global_load_dwordx4 v[78:81], v172, s[40:41] nt
	global_load_dwordx4 v[82:85], v172, s[42:43] nt

; __device__ __forceinline__ u32x4 pack8(const float* f) { u32x4 w; w.x = pk2(f[0], f[1]); w.y = pk2(f[2], f[3]); w.z = pk2(f[4], f[5]); w.w = pk2(f[6], f[7]); return w; }
; __device__ void tconv(unsigned char* smem, const float* src, int ldsrc, int col0, int N, int K, u16* dst, int ldd) {
;     float* T = (float*)smem;
;     const int tid = threadIdx.x, tilesN = N >> 6, ntile = tilesN * (K >> 6);
;     const int lr = tid >> 4, lc = (tid & 15) * 4;
;     const int sn = tid >> 3, sk = (tid & 7) * 8;
;     int tile = blockIdx.x;
;     f32x4 v0 = {0.f, 0.f, 0.f, 0.f}, v1 = {0.f, 0.f, 0.f, 0.f};
;     if (tile < ntile) { const int tn = tile % tilesN, tk = tile / tilesN; const float* s = src + (size_t)(tk * 64 + lr) * ldsrc + col0 + tn * 64 + lc;
;         v0 = __builtin_nontemporal_load((const f32x4*)s); v1 = __builtin_nontemporal_load((const f32x4*)(s + (size_t)32 * ldsrc)); }
;     for (; tile < ntile; tile += gridDim.x) {
;         const int tn = tile % tilesN, tk = tile / tilesN;
; #pragma unroll
;         for (int j = 0; j < 4; ++j) { T[lr * 65 + lc + j] = v0[j]; T[(lr + 32) * 65 + lc + j] = v1[j]; }
;         asm volatile("s_waitcnt lgkmcnt(0)" ::: "memory"); __builtin_amdgcn_s_barrier(); asm volatile("" ::: "memory");
;         const int nx = tile + gridDim.x;
;         if (nx < ntile) { const int tn2 = nx % tilesN, tk2 = nx / tilesN; const float* s = src + (size_t)(tk2 * 64 + lr) * ldsrc + col0 + tn2 * 64 + lc;
;             v0 = __builtin_nontemporal_load((const f32x4*)s); v1 = __builtin_nontemporal_load((const f32x4*)(s + (size_t)32 * ldsrc)); }
;         float f[8];
; #pragma unroll
;         for (int j = 0; j < 8; ++j) f[j] = T[(sk + j) * 65 + sn];
;         *(u32x4*)(dst + (size_t)(tn * 64 + sn) * ldd + tk * 64 + sk) = pack8(f);
;         asm volatile("s_waitcnt lgkmcnt(0)" ::: "memory"); __builtin_amdgcn_s_barrier(); asm volatile("" ::: "memory");
;     }
;     __syncthreads();
; }
.LBB0_674:
	s_or_b64 exec, exec, s[2:3]
	s_cmpk_gt_i32 s70, 0x7ff
	s_cbranch_scc1 .LBB0_681
	s_waitcnt vmcnt(0) lgkmcnt(0)
	s_barrier
	v_readlane_b32 s56, v251, 32
	v_readlane_b32 s57, v251, 33
	v_and_b32_e32 v142, 0x3ff, v0
	v_lshrrev_b32_e32 v153, 4, v142
	v_and_b32_e32 v154, 15, v142
	v_lshlrev_b32_e32 v154, 4, v154
	v_lshlrev_b32_e32 v143, 16, v153
	s_load_dwordx2 s[40:41], s[56:57], 0xc0
	v_add_u32_e32 v143, v143, v154
	v_mul_u32_u24_e32 v145, 0x104, v153
	v_add_u32_e32 v145, v145, v154
	v_add_u32_e32 v146, 0x2080, v145
	v_add_u32_e32 v147, 0x4100, v145
	v_add_u32_e32 v148, 0x6180, v145
	v_lshrrev_b32_e32 v153, 3, v142
	v_and_b32_e32 v154, 7, v142
	v_mul_u32_u24_e32 v149, 0x820, v154
	v_lshl_add_u32 v149, v153, 2, v149
	v_add_u32_e32 v150, 0x400, v149
	v_add_u32_e32 v151, 0x4100, v149
	v_add_u32_e32 v152, 0x4500, v149
	v_lshlrev_b32_e32 v144, 12, v153
	v_lshl_add_u32 v144, v154, 4, v144
	s_add_u32 s44, s64, 0x1e000000
	s_addc_u32 s45, s65, 0
	s_lshl_b32 s54, s62, 1
	s_mov_b32 s46, s70
	s_waitcnt lgkmcnt(0)
	s_add_u32 s40, s40, 0x8000
	s_addc_u32 s41, s41, 0
	s_add_u32 s42, s40, 0x200000
	s_addc_u32 s43, s41, 0
	s_add_i32 s47, s46, s62
	s_cmpk_lt_i32 s47, 0x800
	s_cselect_b32 s47, s47, s46
	s_lshr_b32 s53, s46, 7
	s_and_b32 s52, s46, 3
	s_lshl_b32 s53, s53, 2
	s_or_b32 s52, s52, s53
	s_bfe_u32 s53, s46, 0x50002
	s_lshl_b32 s52, s52, 8
	s_lshl_b32 s53, s53, 22
	s_add_i32 s48, s52, s53
	s_lshr_b32 s53, s47, 7
	s_and_b32 s52, s47, 3
	s_lshl_b32 s53, s53, 2
	s_or_b32 s52, s52, s53
	s_bfe_u32 s53, s47, 0x50002
	s_lshl_b32 s52, s52, 8
	s_lshl_b32 s53, s53, 22
	s_add_i32 s49, s52, s53
	v_add_u32_e32 v153, s48, v143
	v_add_u32_e32 v172, s49, v143
	global_load_dwordx4 v[70:73], v153, s[40:41] nt
	global_load_dwordx4 v[74:77], v153, s[42:43] nt
	global_load_dwordx4 v[78:81], v172, s[40:41] nt
	global_load_dwordx4 v[82:85], v172, s[42:43] nt
	s_waitcnt vmcnt(0)
TCV4_body:
	ds_write2_b32 v145, v70, v71 offset1:1
	ds_write2_b32 v145, v72, v73 offset0:2 offset1:3
	ds_write2_b32 v146, v74, v75 offset1:1
	ds_write2_b32 v146, v76, v77 offset0:2 offset1:3
	ds_write2_b32 v147, v78, v79 offset1:1
	ds_write2_b32 v147, v80, v81 offset0:2 offset1:3
	ds_write2_b32 v148, v82, v83 offset1:1
	ds_write2_b32 v148, v84, v85 offset0:2 offset1:3
	s_lshr_b32 s53, s46, 7
	s_and_b32 s52, s46, 3
	s_lshl_b32 s53, s53, 2
	s_or_b32 s52, s52, s53
	s_bfe_u32 s53, s46, 0x50002
	s_lshl_b32 s52, s52, 18
	s_lshl_b32 s53, s53, 7
	s_add_i32 s50, s52, s53
	s_lshr_b32 s53, s47, 7
	s_and_b32 s52, s47, 3
	s_lshl_b32 s53, s53, 2
	s_or_b32 s52, s52, s53
	s_bfe_u32 s53, s47, 0x50002
	s_lshl_b32 s52, s52, 18
	s_lshl_b32 s53, s53, 7
	s_add_i32 s51, s52, s53
	s_waitcnt lgkmcnt(0)
	s_barrier
	s_add_i32 s46, s46, s54
	s_cmpk_lt_i32 s46, 0x800
	s_cbranch_scc0 TCV4_noload
	s_add_i32 s47, s46, s62
	s_cmpk_lt_i32 s47, 0x800
	s_cselect_b32 s47, s47, s46
	s_lshr_b32 s53, s46, 7
	s_and_b32 s52, s46, 3
	s_lshl_b32 s53, s53, 2
	s_or_b32 s52, s52, s53
	s_bfe_u32 s53, s46, 0x50002
	s_lshl_b32 s52, s52, 8
	s_lshl_b32 s53, s53, 22
	s_add_i32 s48, s52, s53
	s_lshr_b32 s53, s47, 7
	s_and_b32 s52, s47, 3
	s_lshl_b32 s53, s53, 2
	s_or_b32 s52, s52, s53
	s_bfe_u32 s53, s47, 0x50002
	s_lshl_b32 s52, s52, 8
	s_lshl_b32 s53, s53, 22
	s_add_i32 s49, s52, s53
	v_add_u32_e32 v153, s48, v143
	v_add_u32_e32 v172, s49, v143
	global_load_dwordx4 v[70:73], v153, s[40:41] nt
	global_load_dwordx4 v[74:77], v153, s[42:43] nt
	global_load_dwordx4 v[78:81], v172, s[40:41] nt
	global_load_dwordx4 v[82:85], v172, s[42:43] nt

; __device__ __forceinline__ u32x4 pack8(const float* f) { u32x4 w; w.x = pk2(f[0], f[1]); w.y = pk2(f[2], f[3]); w.z = pk2(f[4], f[5]); w.w = pk2(f[6], f[7]); return w; }
; __device__ void tconv(unsigned char* smem, const float* src, int ldsrc, int col0, int N, int K, u16* dst, int ldd) {
;     float* T = (float*)smem;
;     const int tid = threadIdx.x, tilesN = N >> 6, ntile = tilesN * (K >> 6);
;     const int lr = tid >> 4, lc = (tid & 15) * 4;
;     const int sn = tid >> 3, sk = (tid & 7) * 8;
;     int tile = blockIdx.x;
;     f32x4 v0 = {0.f, 0.f, 0.f, 0.f}, v1 = {0.f, 0.f, 0.f, 0.f};
;     if (tile < ntile) { const int tn = tile % tilesN, tk = tile / tilesN; const float* s = src + (size_t)(tk * 64 + lr) * ldsrc + col0 + tn * 64 + lc;
;         v0 = __builtin_nontemporal_load((const f32x4*)s); v1 = __builtin_nontemporal_load((const f32x4*)(s + (size_t)32 * ldsrc)); }
;     for (; tile < ntile; tile += gridDim.x) {
;         const int tn = tile % tilesN, tk = tile / tilesN;
; #pragma unroll
;         for (int j = 0; j < 4; ++j) { T[lr * 65 + lc + j] = v0[j]; T[(lr + 32) * 65 + lc + j] = v1[j]; }
;         asm volatile("s_waitcnt lgkmcnt(0)" ::: "memory"); __builtin_amdgcn_s_barrier(); asm volatile("" ::: "memory");
;         const int nx = tile + gridDim.x;
;         if (nx < ntile) { const int tn2 = nx % tilesN, tk2 = nx / tilesN; const float* s = src + (size_t)(tk2 * 64 + lr) * ldsrc + col0 + tn2 * 64 + lc;
;             v0 = __builtin_nontemporal_load((const f32x4*)s); v1 = __builtin_nontemporal_load((const f32x4*)(s + (size_t)32 * ldsrc)); }
;         float f[8];
; #pragma unroll
;         for (int j = 0; j < 8; ++j) f[j] = T[(sk + j) * 65 + sn];
;         *(u32x4*)(dst + (size_t)(tn * 64 + sn) * ldd + tk * 64 + sk) = pack8(f);
;         asm volatile("s_waitcnt lgkmcnt(0)" ::: "memory"); __builtin_amdgcn_s_barrier(); asm volatile("" ::: "memory");
;     }
;     __syncthreads();
; }
.LBB0_1013:
	s_cmpk_lt_i32 s70, 0x800
	v_lshrrev_b32_e32 v1, 4, v103
	s_cselect_b64 s[0:1], -1, 0
	s_cmpk_gt_i32 s70, 0x7ff
	v_lshrrev_b32_e32 v14, 3, v103
	s_cbranch_scc1 .LBB0_1020
	s_waitcnt vmcnt(0) lgkmcnt(0)
	s_barrier
	v_readlane_b32 s40, v251, 28
	v_readlane_b32 s41, v251, 29
	v_and_b32_e32 v142, 0x3ff, v0
	v_lshrrev_b32_e32 v153, 4, v142
	v_and_b32_e32 v154, 15, v142
	v_lshlrev_b32_e32 v154, 4, v154
	v_lshlrev_b32_e32 v143, 16, v153
	v_add_u32_e32 v143, v143, v154
	v_mul_u32_u24_e32 v145, 0x104, v153
	v_add_u32_e32 v145, v145, v154
	v_add_u32_e32 v146, 0x2080, v145
	v_add_u32_e32 v147, 0x4100, v145
	v_add_u32_e32 v148, 0x6180, v145
	v_lshrrev_b32_e32 v153, 3, v142
	v_and_b32_e32 v154, 7, v142
	v_mul_u32_u24_e32 v149, 0x820, v154
	v_lshl_add_u32 v149, v153, 2, v149
	v_add_u32_e32 v150, 0x400, v149
	v_add_u32_e32 v151, 0x4100, v149
	v_add_u32_e32 v152, 0x4500, v149
	v_lshlrev_b32_e32 v144, 12, v153
	v_lshl_add_u32 v144, v154, 4, v144
	s_add_u32 s44, s64, 0x1c000000
	s_addc_u32 s45, s65, 0
	s_lshl_b32 s54, s62, 1
	s_mov_b32 s46, s70
	s_waitcnt lgkmcnt(0)
	s_add_u32 s40, s40, 0xc000
	s_addc_u32 s41, s41, 0
	s_add_u32 s42, s40, 0x200000
	s_addc_u32 s43, s41, 0
	s_add_i32 s47, s46, s62
	s_cmpk_lt_i32 s47, 0x800
	s_cselect_b32 s47, s47, s46
	s_lshr_b32 s53, s46, 7
	s_and_b32 s52, s46, 3
	s_lshl_b32 s53, s53, 2
	s_or_b32 s52, s52, s53
	s_bfe_u32 s53, s46, 0x50002
	s_lshl_b32 s52, s52, 8
	s_lshl_b32 s53, s53, 22
	s_add_i32 s48, s52, s53
	s_lshr_b32 s53, s47, 7
	s_and_b32 s52, s47, 3
	s_lshl_b32 s53, s53, 2
	s_or_b32 s52, s52, s53
	s_bfe_u32 s53, s47, 0x50002
	s_lshl_b32 s52, s52, 8
	s_lshl_b32 s53, s53, 22
	s_add_i32 s49, s52, s53
	v_add_u32_e32 v153, s48, v143
	v_add_u32_e32 v172, s49, v143
	global_load_dwordx4 v[70:73], v153, s[40:41] nt
	global_load_dwordx4 v[74:77], v153, s[42:43] nt
	global_load_dwordx4 v[78:81], v172, s[40:41] nt
	global_load_dwordx4 v[82:85], v172, s[42:43] nt
	s_waitcnt vmcnt(0)
TCV5_body:
	ds_write2_b32 v145, v70, v71 offset1:1
	ds_write2_b32 v145, v72, v73 offset0:2 offset1:3
	ds_write2_b32 v146, v74, v75 offset1:1
	ds_write2_b32 v146, v76, v77 offset0:2 offset1:3
	ds_write2_b32 v147, v78, v79 offset1:1
	ds_write2_b32 v147, v80, v81 offset0:2 offset1:3
	ds_write2_b32 v148, v82, v83 offset1:1
	ds_write2_b32 v148, v84, v85 offset0:2 offset1:3
	s_lshr_b32 s53, s46, 7
	s_and_b32 s52, s46, 3
	s_lshl_b32 s53, s53, 2
	s_or_b32 s52, s52, s53
	s_bfe_u32 s53, s46, 0x50002
	s_lshl_b32 s52, s52, 18
	s_lshl_b32 s53, s53, 7
	s_add_i32 s50, s52, s53
	s_lshr_b32 s53, s47, 7
	s_and_b32 s52, s47, 3
	s_lshl_b32 s53, s53, 2
	s_or_b32 s52, s52, s53
	s_bfe_u32 s53, s47, 0x50002
	s_lshl_b32 s52, s52, 18
	s_lshl_b32 s53, s53, 7
	s_add_i32 s51, s52, s53
	s_waitcnt lgkmcnt(0)
	s_barrier
	s_add_i32 s46, s46, s54
	s_cmpk_lt_i32 s46, 0x800
	s_cbranch_scc0 TCV5_noload
	s_add_i32 s47, s46, s62
	s_cmpk_lt_i32 s47, 0x800
	s_cselect_b32 s47, s47, s46
	s_lshr_b32 s53, s46, 7
	s_and_b32 s52, s46, 3
	s_lshl_b32 s53, s53, 2
	s_or_b32 s52, s52, s53
	s_bfe_u32 s53, s46, 0x50002
	s_lshl_b32 s52, s52, 8
	s_lshl_b32 s53, s53, 22
	s_add_i32 s48, s52, s53
	s_lshr_b32 s53, s47, 7
	s_and_b32 s52, s47, 3
	s_lshl_b32 s53, s53, 2
	s_or_b32 s52, s52, s53
	s_bfe_u32 s53, s47, 0x50002
	s_lshl_b32 s52, s52, 8
	s_lshl_b32 s53, s53, 22
	s_add_i32 s49, s52, s53
	v_add_u32_e32 v153, s48, v143
	v_add_u32_e32 v172, s49, v143
	global_load_dwordx4 v[70:73], v153, s[40:41] nt
	global_load_dwordx4 v[74:77], v153, s[42:43] nt
	global_load_dwordx4 v[78:81], v172, s[40:41] nt
	global_load_dwordx4 v[82:85], v172, s[42:43] nt

; __device__ __forceinline__ u32x4 pack8(const float* f) { u32x4 w; w.x = pk2(f[0], f[1]); w.y = pk2(f[2], f[3]); w.z = pk2(f[4], f[5]); w.w = pk2(f[6], f[7]); return w; }
; __device__ void tconv(unsigned char* smem, const float* src, int ldsrc, int col0, int N, int K, u16* dst, int ldd) {
;     float* T = (float*)smem;
;     const int tid = threadIdx.x, tilesN = N >> 6, ntile = tilesN * (K >> 6);
;     const int lr = tid >> 4, lc = (tid & 15) * 4;
;     const int sn = tid >> 3, sk = (tid & 7) * 8;
;     int tile = blockIdx.x;
;     f32x4 v0 = {0.f, 0.f, 0.f, 0.f}, v1 = {0.f, 0.f, 0.f, 0.f};
;     if (tile < ntile) { const int tn = tile % tilesN, tk = tile / tilesN; const float* s = src + (size_t)(tk * 64 + lr) * ldsrc + col0 + tn * 64 + lc;
;         v0 = __builtin_nontemporal_load((const f32x4*)s); v1 = __builtin_nontemporal_load((const f32x4*)(s + (size_t)32 * ldsrc)); }
;     for (; tile < ntile; tile += gridDim.x) {
;         const int tn = tile % tilesN, tk = tile / tilesN;
; #pragma unroll
;         for (int j = 0; j < 4; ++j) { T[lr * 65 + lc + j] = v0[j]; T[(lr + 32) * 65 + lc + j] = v1[j]; }
;         asm volatile("s_waitcnt lgkmcnt(0)" ::: "memory"); __builtin_amdgcn_s_barrier(); asm volatile("" ::: "memory");
;         const int nx = tile + gridDim.x;
;         if (nx < ntile) { const int tn2 = nx % tilesN, tk2 = nx / tilesN; const float* s = src + (size_t)(tk2 * 64 + lr) * ldsrc + col0 + tn2 * 64 + lc;
;             v0 = __builtin_nontemporal_load((const f32x4*)s); v1 = __builtin_nontemporal_load((const f32x4*)(s + (size_t)32 * ldsrc)); }
;         float f[8];
; #pragma unroll
;         for (int j = 0; j < 8; ++j) f[j] = T[(sk + j) * 65 + sn];
;         *(u32x4*)(dst + (size_t)(tn * 64 + sn) * ldd + tk * 64 + sk) = pack8(f);
;         asm volatile("s_waitcnt lgkmcnt(0)" ::: "memory"); __builtin_amdgcn_s_barrier(); asm volatile("" ::: "memory");
;     }
;     __syncthreads();
; }
.LBB0_1020:
	s_andn2_b64 vcc, exec, s[0:1]
	s_barrier
	s_cbranch_vccnz .LBB0_1027
	s_waitcnt vmcnt(0) lgkmcnt(0)
	s_barrier
	v_readlane_b32 s40, v250, 15
	v_readlane_b32 s41, v250, 16
	v_and_b32_e32 v142, 0x3ff, v0
	v_lshrrev_b32_e32 v153, 4, v142
	v_and_b32_e32 v154, 15, v142
	v_lshlrev_b32_e32 v154, 4, v154
	v_lshlrev_b32_e32 v143, 13, v153
	v_add_u32_e32 v143, v143, v154
	v_mul_u32_u24_e32 v145, 0x104, v153
	v_add_u32_e32 v145, v145, v154
	v_add_u32_e32 v146, 0x2080, v145
	v_add_u32_e32 v147, 0x4100, v145
	v_add_u32_e32 v148, 0x6180, v145
	v_lshrrev_b32_e32 v153, 3, v142
	v_and_b32_e32 v154, 7, v142
	v_mul_u32_u24_e32 v149, 0x820, v154
	v_lshl_add_u32 v149, v153, 2, v149
	v_add_u32_e32 v150, 0x400, v149
	v_add_u32_e32 v151, 0x4100, v149
	v_add_u32_e32 v152, 0x4500, v149
	v_lshlrev_b32_e32 v144, 13, v153
	v_lshl_add_u32 v144, v154, 4, v144
	s_add_u32 s44, s64, 0x1d000000
	s_addc_u32 s45, s65, 0
	s_lshl_b32 s54, s62, 1
	s_mov_b32 s46, s70
	s_waitcnt lgkmcnt(0)
	s_add_u32 s42, s40, 0x40000
	s_addc_u32 s43, s41, 0
	s_add_i32 s47, s46, s62
	s_cmpk_lt_i32 s47, 0x800
	s_cselect_b32 s47, s47, s46
	s_lshr_b32 s53, s46, 8
	s_and_b32 s52, s46, 3
	s_lshl_b32 s53, s53, 2
	s_or_b32 s52, s52, s53
	s_bfe_u32 s53, s46, 0x60002
	s_lshl_b32 s52, s52, 8
	s_lshl_b32 s53, s53, 19
	s_add_i32 s48, s52, s53
	s_lshr_b32 s53, s47, 8
	s_and_b32 s52, s47, 3
	s_lshl_b32 s53, s53, 2
	s_or_b32 s52, s52, s53
	s_bfe_u32 s53, s47, 0x60002
	s_lshl_b32 s52, s52, 8
	s_lshl_b32 s53, s53, 19
	s_add_i32 s49, s52, s53
	v_add_u32_e32 v153, s48, v143
	v_add_u32_e32 v172, s49, v143
	global_load_dwordx4 v[70:73], v153, s[40:41] nt
	global_load_dwordx4 v[74:77], v153, s[42:43] nt
	global_load_dwordx4 v[78:81], v172, s[40:41] nt
	global_load_dwordx4 v[82:85], v172, s[42:43] nt
	s_waitcnt vmcnt(0)
TCV6_body:
	ds_write2_b32 v145, v70, v71 offset1:1
	ds_write2_b32 v145, v72, v73 offset0:2 offset1:3
	ds_write2_b32 v146, v74, v75 offset1:1
	ds_write2_b32 v146, v76, v77 offset0:2 offset1:3
	ds_write2_b32 v147, v78, v79 offset1:1
	ds_write2_b32 v147, v80, v81 offset0:2 offset1:3
	ds_write2_b32 v148, v82, v83 offset1:1
	ds_write2_b32 v148, v84, v85 offset0:2 offset1:3
	s_lshr_b32 s53, s46, 8
	s_and_b32 s52, s46, 3
	s_lshl_b32 s53, s53, 2
	s_or_b32 s52, s52, s53
	s_bfe_u32 s53, s46, 0x60002
	s_lshl_b32 s52, s52, 19
	s_lshl_b32 s53, s53, 7
	s_add_i32 s50, s52, s53
	s_lshr_b32 s53, s47, 8
	s_and_b32 s52, s47, 3
	s_lshl_b32 s53, s53, 2
	s_or_b32 s52, s52, s53
	s_bfe_u32 s53, s47, 0x60002
	s_lshl_b32 s52, s52, 19
	s_lshl_b32 s53, s53, 7
	s_add_i32 s51, s52, s53
	s_waitcnt lgkmcnt(0)
	s_barrier
	s_add_i32 s46, s46, s54
	s_cmpk_lt_i32 s46, 0x800
	s_cbranch_scc0 TCV6_noload
	s_add_i32 s47, s46, s62
	s_cmpk_lt_i32 s47, 0x800
	s_cselect_b32 s47, s47, s46
	s_lshr_b32 s53, s46, 8
	s_and_b32 s52, s46, 3
	s_lshl_b32 s53, s53, 2
	s_or_b32 s52, s52, s53
	s_bfe_u32 s53, s46, 0x60002
	s_lshl_b32 s52, s52, 8
	s_lshl_b32 s53, s53, 19
	s_add_i32 s48, s52, s53
	s_lshr_b32 s53, s47, 8
	s_and_b32 s52, s47, 3
	s_lshl_b32 s53, s53, 2
	s_or_b32 s52, s52, s53
	s_bfe_u32 s53, s47, 0x60002
	s_lshl_b32 s52, s52, 8
	s_lshl_b32 s53, s53, 19
	s_add_i32 s49, s52, s53
	v_add_u32_e32 v153, s48, v143
	v_add_u32_e32 v172, s49, v143
	global_load_dwordx4 v[70:73], v153, s[40:41] nt
	global_load_dwordx4 v[74:77], v153, s[42:43] nt
	global_load_dwordx4 v[78:81], v172, s[40:41] nt
	global_load_dwordx4 v[82:85], v172, s[42:43] nt
